# HGRN output pass: per-row store addresses stepped incrementally (one 64-bit add per store instead of seven VALU), on top of previous version
# baseline (speedup 1.0000x reference)
; __device__ __forceinline__ int crow(int r, int hi) { return (r & 3) + 8 * (r >> 2) + 4 * hi; }
; __device__ __forceinline__ unsigned cvtpk(float lo, float hi) { unsigned r; asm volatile("v_cvt_pk_bf16_f32 %0, %1, %2" : "=v"(r) : "v"(lo), "v"(hi)); return r; }
; __device__ __forceinline__ int crow(int r, int hi) { return (r & 3) + 8 * (r >> 2) + 4 * hi; }
; __device__ __forceinline__ unsigned cvtpk(float lo, float hi) { unsigned r; asm volatile("v_cvt_pk_bf16_f32 %0, %1, %2" : "=v"(r) : "v"(lo), "v"(hi)); return r; }
; template <int MODE> __device__ __forceinline__ void chain(const bf16_t* __restrict__ U, bf16_t* __restrict__ OP, const float* __restrict__ hg_lb, int rowbase, int S, int h, int dir, int tau0, int nchunk, ...
;     ...
; #pragma unroll
;       for (int i = 0; i < 2; ++i)
; #pragma unroll
;         for (int r = 0; r < 16; ++r) sacc[i][r] = slot_in[(32 * (wid & 3) + crow(r, hi)) * 128 + 32 * (2 * (wid >> 2) + i) + r32];
;     }
; #pragma unroll
;     for (int i = 0; i < 2; ++i)
; #pragma unroll
;       for (int r = 0; r < 16; ++r) *(bf16_t*)(ST + SWZ256(32 * (wid & 3) + crow(r, hi), 2 * (32 * (2 * (wid >> 2) + i) + r32))) = (bf16_t)(cvtpk(sacc[i][r], 0.f) & 0xffffu);
.LBB0_823:
	s_lshl_b32 s6, s18, 6
	v_lshlrev_b32_e32 v56, 1, v59
	s_and_b32 s6, s6, 0xffffff80
	v_or_b32_e32 v33, s6, v56
	v_lshlrev_b32_e32 v61, 6, v58
	v_lshl_add_u32 v32, v32, 8, 0
	v_add3_u32 v35, v32, v61, v33
	v_or_b32_e32 v63, 1, v60
	s_waitcnt vmcnt(31)
	v_cvt_pk_bf16_f32 v34, v0, v85
	ds_write_b16 v35, v34
	v_or_b32_e32 v35, s8, v63
	v_lshlrev_b32_e32 v62, 4, v63
	v_lshl_add_u32 v35, v35, 8, 0
	v_xad_u32 v36, v33, v62, v35
	v_or_b32_e32 v66, 2, v60
	s_waitcnt vmcnt(30)
	v_cvt_pk_bf16_f32 v34, v1, v85
	ds_write_b16 v36, v34
	v_or_b32_e32 v36, s8, v66
	v_lshlrev_b32_e32 v67, 4, v66
	v_lshl_add_u32 v36, v36, 8, 0
	v_xad_u32 v37, v33, v67, v36
	v_or_b32_e32 v68, 3, v60
	s_waitcnt vmcnt(29)
	v_cvt_pk_bf16_f32 v34, v2, v85
	ds_write_b16 v37, v34
	v_or_b32_e32 v37, s8, v68
	v_lshlrev_b32_e32 v69, 4, v68
	v_lshl_add_u32 v37, v37, 8, 0
	v_xad_u32 v38, v33, v69, v37
	v_or_b32_e32 v70, 8, v60
	s_waitcnt vmcnt(28)
	v_cvt_pk_bf16_f32 v34, v3, v85
	ds_write_b16 v38, v34
	v_or_b32_e32 v38, s8, v70
	v_lshlrev_b32_e32 v71, 4, v70
	v_and_b32_e32 v72, 64, v71
	v_lshl_add_u32 v38, v38, 8, 0
	v_add3_u32 v39, v38, v72, v33
	v_or_b32_e32 v73, 9, v60
	s_waitcnt vmcnt(27)
	v_cvt_pk_bf16_f32 v34, v4, v85
	ds_write_b16 v39, v34
	v_or_b32_e32 v39, s8, v73
	v_lshlrev_b32_e32 v74, 4, v73
	v_and_b32_e32 v40, 0x50, v74
	v_lshl_add_u32 v39, v39, 8, 0
	v_xad_u32 v41, v33, v40, v39
	v_or_b32_e32 v75, 10, v60
	s_waitcnt vmcnt(26)
	v_cvt_pk_bf16_f32 v34, v5, v85
	ds_write_b16 v41, v34
	v_or_b32_e32 v41, s8, v75
	v_lshlrev_b32_e32 v76, 4, v75
	v_and_b32_e32 v42, 0x60, v76
	v_lshl_add_u32 v41, v41, 8, 0
	v_xad_u32 v43, v33, v42, v41
	v_or_b32_e32 v77, 11, v60
	s_waitcnt vmcnt(25)
	v_cvt_pk_bf16_f32 v34, v6, v85
	ds_write_b16 v43, v34
	v_or_b32_e32 v43, s8, v77
	v_lshlrev_b32_e32 v78, 4, v77
	v_and_b32_e32 v44, 0x70, v78
	v_lshl_add_u32 v43, v43, 8, 0
	v_xad_u32 v45, v33, v44, v43
	v_or_b32_e32 v79, 16, v60
	s_waitcnt vmcnt(24)
	v_cvt_pk_bf16_f32 v34, v7, v85
	ds_write_b16 v45, v34
	v_or_b32_e32 v45, s8, v79
	v_lshlrev_b32_e32 v80, 4, v79
	v_and_b32_e32 v81, 64, v80
	v_lshl_add_u32 v45, v45, 8, 0
	v_add3_u32 v46, v45, v81, v33
	v_or_b32_e32 v82, 17, v60
	s_waitcnt vmcnt(23)
	v_cvt_pk_bf16_f32 v34, v8, v85
	ds_write_b16 v46, v34
	v_or_b32_e32 v46, s8, v82
	v_lshlrev_b32_e32 v83, 4, v82
	v_and_b32_e32 v47, 0x50, v83
	v_lshl_add_u32 v46, v46, 8, 0
	s_waitcnt vmcnt(17)
	v_xad_u32 v48, v33, v47, v46
	v_or_b32_e32 v154, 18, v60
	s_waitcnt vmcnt(22)
	v_cvt_pk_bf16_f32 v34, v9, v85
	ds_write_b16 v48, v34
	v_or_b32_e32 v48, s8, v154
	v_lshlrev_b32_e32 v155, 4, v154
	v_and_b32_e32 v49, 0x60, v155
	v_lshl_add_u32 v48, v48, 8, 0
	v_xad_u32 v50, v33, v49, v48
	v_or_b32_e32 v156, 19, v60
	s_waitcnt vmcnt(21)
	v_cvt_pk_bf16_f32 v34, v10, v85
	ds_write_b16 v50, v34
	v_or_b32_e32 v50, s8, v156
	v_lshlrev_b32_e32 v157, 4, v156
	v_and_b32_e32 v51, 0x70, v157
	v_lshl_add_u32 v50, v50, 8, 0
	s_waitcnt vmcnt(16)
	v_xad_u32 v52, v33, v51, v50
	v_or_b32_e32 v158, 24, v60
	s_waitcnt vmcnt(20)
	v_cvt_pk_bf16_f32 v34, v11, v85
	ds_write_b16 v52, v34
	v_or_b32_e32 v52, s8, v158
	v_lshlrev_b32_e32 v159, 4, v158
	v_and_b32_e32 v160, 64, v159
	v_lshl_add_u32 v52, v52, 8, 0
	v_add3_u32 v53, v52, v160, v33
	v_or_b32_e32 v161, 25, v60
	s_waitcnt vmcnt(19)
	v_cvt_pk_bf16_f32 v34, v12, v85
	ds_write_b16 v53, v34
	v_or_b32_e32 v53, s8, v161
	v_lshlrev_b32_e32 v162, 4, v161
	v_and_b32_e32 v54, 0x50, v162
	v_lshl_add_u32 v53, v53, 8, 0
	v_xad_u32 v55, v33, v54, v53
	v_or_b32_e32 v163, 26, v60
	s_waitcnt vmcnt(18)
	v_cvt_pk_bf16_f32 v34, v13, v85
	ds_write_b16 v55, v34
	v_or_b32_e32 v55, s8, v163
	v_lshlrev_b32_e32 v164, 4, v163
	v_and_b32_e32 v64, 0x60, v164
	v_lshl_add_u32 v55, v55, 8, 0
	v_xad_u32 v65, v33, v64, v55
	v_or_b32_e32 v165, 27, v60
	s_waitcnt vmcnt(17)
	v_cvt_pk_bf16_f32 v34, v14, v85
	ds_write_b16 v65, v34
	v_or_b32_e32 v65, s8, v165
	v_lshlrev_b32_e32 v166, 4, v165
	v_and_b32_e32 v84, 0x70, v166
	v_lshl_add_u32 v65, v65, 8, 0
	s_waitcnt vmcnt(16)
	v_cvt_pk_bf16_f32 v34, v15, v85
	v_xad_u32 v86, v33, v84, v65
	v_or_b32_e32 v33, 64, v33
	ds_write_b16 v86, v34
	s_waitcnt vmcnt(15)
	v_cvt_pk_bf16_f32 v34, v16, v85
	v_xad_u32 v32, v33, v61, v32
	ds_write_b16 v32, v34
	v_xad_u32 v34, v33, v62, v35
	s_waitcnt vmcnt(14)
	v_cvt_pk_bf16_f32 v32, v17, v85
	ds_write_b16 v34, v32
	v_xad_u32 v34, v33, v67, v36
	s_waitcnt vmcnt(13)
	v_cvt_pk_bf16_f32 v32, v18, v85
	ds_write_b16 v34, v32
	v_xad_u32 v34, v33, v69, v37
	s_waitcnt vmcnt(12)
	v_cvt_pk_bf16_f32 v32, v19, v85
	ds_write_b16 v34, v32
	v_xad_u32 v34, v33, v72, v38
	s_waitcnt vmcnt(11)
	v_cvt_pk_bf16_f32 v32, v20, v85
	ds_write_b16 v34, v32
	v_xad_u32 v34, v33, v40, v39
	s_waitcnt vmcnt(10)
	v_cvt_pk_bf16_f32 v32, v21, v85
	ds_write_b16 v34, v32
	v_xad_u32 v34, v33, v42, v41
	s_waitcnt vmcnt(9)
	v_cvt_pk_bf16_f32 v32, v22, v85
	ds_write_b16 v34, v32
	v_xad_u32 v34, v33, v44, v43
	s_waitcnt vmcnt(8)
	v_cvt_pk_bf16_f32 v32, v23, v85
	ds_write_b16 v34, v32
	v_xad_u32 v34, v33, v81, v45
	s_waitcnt vmcnt(7)
	v_cvt_pk_bf16_f32 v32, v24, v85
	ds_write_b16 v34, v32
	v_xad_u32 v34, v33, v47, v46
	s_lshl_b32 s19, s9, 10
	s_waitcnt vmcnt(6)
	v_cvt_pk_bf16_f32 v32, v25, v85
	ds_write_b16 v34, v32
	v_xad_u32 v34, v33, v49, v48
	s_mul_i32 s7, s96, 0x1400
	s_waitcnt vmcnt(5)
	v_cvt_pk_bf16_f32 v32, v26, v85
	ds_write_b16 v34, v32
	v_xad_u32 v34, v33, v51, v50
	s_mul_hi_i32 s6, s96, 0x1400
	s_add_u32 s7, s64, s7
	s_waitcnt vmcnt(4)
	v_cvt_pk_bf16_f32 v32, v27, v85
	ds_write_b16 v34, v32
	v_xad_u32 v34, v33, v160, v52
	v_lshlrev_b32_e32 v167, 4, v57
	s_addc_u32 s8, s65, s6
	s_lshl_b32 s72, s11, 8
	s_waitcnt vmcnt(3)
; __device__ __forceinline__ int crow(int r, int hi) { return (r & 3) + 8 * (r >> 2) + 4 * hi; }
; __device__ __forceinline__ int crow(int r, int hi) { return (r & 3) + 8 * (r >> 2) + 4 * hi; }
; __device__ __forceinline__ unsigned cvtpk_m(float lo, float hi) { f32x2_t v = {lo, hi}; bf16x2_t b = __builtin_convertvector(v, bf16x2_t); return __builtin_bit_cast(unsigned, b); }
; template <int MODE> __device__ __forceinline__ void chain(const bf16_t* __restrict__ U, bf16_t* __restrict__ OP, const float* __restrict__ hg_lb, int rowbase, int S, int h, int dir, int tau0, int nchunk, ...
;     ...
;   float dseg = 1.0f;
;   const int tau = tid >> 3, c0 = (tid & 7) * 16, segt = tau >> 4;
;   const bf16_t* Ub = U + (size_t)rowbase * 2560 + h * 128 + c0;
;   const size_t offq = 0, offv = 512, offf = (size_t)(2 + dir) * 512;
;   bf16_t* OPd = OP + (size_t)dir * T_ALL * 512;
;   bf16x8 nq0 = {}, nq1 = {}, nv0, nv1, nf0, nf1;
;   { const int t1 = tau0 + tau; const int tok = dir ? (S - 1 - t1) : t1; const bf16_t* p = Ub + (size_t)tok * 2560;
;     if (MODE == 3) { nq0 = *(const bf16x8*)(p + offq); nq1 = *(const bf16x8*)(p + offq + 8); } nv0 = *(const bf16x8*)(p + offv); nv1 = *(const bf16x8*)(p + offv + 8); nf0 = *(const bf16x8*)(p + offf); nf1 = *(const bf16x8*)(p + offf + 8); }
;     ...
;       for (int r = 0; r < 16; ++r) { const int t2 = tau0 + ci * 64 + 32 * th + crow(r, hi); const int tok = dir ? (S - 1 - t2) : t2;
;         OPd[(size_t)(rowbase + tok) * 512 + h * 128 + 32 * vb + r32] = (bf16_t)(cvtpk_m(o[r], 0.f) & 0xffffu); }
	v_cvt_pk_bf16_f32 v32, v28, v85
	ds_write_b16 v34, v32
	v_xad_u32 v34, v33, v54, v53
	v_and_b32_e32 v151, 0x70, v167
	s_add_u32 s6, s7, s72
	s_waitcnt vmcnt(2)
	v_cvt_pk_bf16_f32 v32, v29, v85
	ds_write_b16 v34, v32
	v_xad_u32 v34, v33, v64, v55
	v_xad_u32 v33, v33, v84, v65
	s_addc_u32 s7, s8, 0
	v_lshlrev_b32_e32 v84, 1, v151
	v_lshl_add_u64 v[86:87], s[6:7], 0, v[84:85]
	s_lshl_b32 s78, s10, 9
	s_mul_i32 s6, s10, 0x6000000
	s_add_u32 s24, s52, s6
	s_waitcnt vmcnt(1)
	v_cvt_pk_bf16_f32 v32, v30, v85
	v_ashrrev_i32_e32 v106, 3, v57
	s_addc_u32 s25, s53, 0
	ds_write_b16 v34, v32
	s_waitcnt vmcnt(0)
	v_cvt_pk_bf16_f32 v32, v31, v85
	v_add_u32_e32 v94, s19, v106
	s_cmp_eq_u32 s10, 0
	ds_write_b16 v33, v32
	v_xad_u32 v32, v94, -1, s97
	s_cselect_b64 s[6:7], -1, 0
	v_cndmask_b32_e64 v32, v32, v94, s[6:7]
	v_mov_b32_e32 v248, 0xfffffc00
	v_mov_b32_e32 v250, 0xffffec00
	v_mov_b32_e32 v249, 0x400
	v_mov_b32_e32 v251, 0x1400
	v_cndmask_b32_e64 v248, v248, v249, s[6:7]
	v_cndmask_b32_e64 v250, v250, v251, s[6:7]
	v_cndmask_b32_e64 v249, -1, 0, s[6:7]
	v_mov_b32_e32 v251, v249
	v_mad_i64_i32 v[48:49], s[8:9], v32, s84, v[86:87]
	global_load_dwordx4 v[44:47], v[48:49], off
	global_load_dwordx4 v[36:39], v[48:49], off offset:16
	global_load_dwordx4 v[40:43], v[48:49], off offset:1024
	global_load_dwordx4 v[32:35], v[48:49], off offset:1040
	s_lshl_b32 s8, s10, 10
	s_mov_b32 s9, s73
	v_lshl_add_u64 v[52:53], v[48:49], 0, s[8:9]
	global_load_dwordx4 v[48:51], v[52:53], off offset:2048
	s_nop 0
	global_load_dwordx4 v[52:55], v[52:53], off offset:2064
	v_lshlrev_b32_e32 v109, 2, v151
	v_add_u32_e32 v88, s86, v109
	v_ashrrev_i32_e32 v64, 7, v57
	v_mad_u64_u32 v[90:91], s[8:9], v106, s87, v[88:89]
	s_cmp_lt_i32 s17, 4
	v_and_b32_e32 v65, 0x7f, v57
	v_cmp_lt_i32_e64 s[8:9], 0, v64
	v_cmp_lt_i32_e64 s[10:11], 1, v64
	v_cmp_lt_i32_e64 s[12:13], 2, v64
	v_lshlrev_b32_e32 v64, 4, v106
	s_cselect_b64 s[20:21], -1, 0
	s_cmp_lg_u32 s17, 1
	v_lshl_add_u32 v168, v65, 2, s86
	v_lshl_add_u32 v91, v57, 2, s88
	v_lshlrev_b32_e32 v57, 8, v106
	v_and_b32_e32 v64, 0x70, v64
	v_or_b32_e32 v65, 16, v84
	s_cselect_b64 s[22:23], -1, 0
	s_lshl_b32 s18, s18, 13
	v_bitop3_b32 v169, v84, v57, v64 bitop3:0xde
	v_bitop3_b32 v170, v65, v57, v64 bitop3:0xde
	s_and_b64 s[76:77], s[20:21], s[22:23]
	s_and_b32 s20, s17, 1
	v_lshlrev_b32_e32 v57, 8, v59
	s_add_i32 s18, s18, 0
	v_add_u32_e32 v96, s18, v57
	s_lshl_b32 s18, s20, 13
	s_add_i32 s18, s18, 0
	s_ashr_i32 s59, s16, 8
	s_and_b32 s17, s17, 3
	s_cmpk_lt_u32 s16, 0x100
	s_cselect_b32 s75, 2, 4
	s_lshl_b32 s16, s59, 5
	v_add_u32_e32 v97, s18, v57
	v_or_b32_e32 v64, s16, v59
	s_lshl_b32 s18, s17, 5
	v_bitop3_b32 v98, v64, s83, v167 bitop3:0x48
	v_lshl_add_u32 v99, v64, 7, s86
	v_or_b32_e32 v64, s18, v59
	v_bitop3_b32 v171, s18, v167, v59 bitop3:0x36
	s_lshl_b32 s18, s59, 13
	s_add_i32 s18, s18, 0
	v_add_u32_e32 v102, s18, v57
	s_lshl_b32 s18, s17, 13
	s_add_i32 s16, s16, s19
	s_add_i32 s58, s18, 0
	v_or_b32_e32 v104, s16, v60
	s_lshl_b32 s16, s17, 6
	s_add_u32 s16, s24, s16
	v_add_u32_e32 v103, s58, v57
	s_addc_u32 s17, s25, 0
	v_mov_b32_e32 v57, v85
	v_bitop3_b32 v100, v64, s83, v167 bitop3:0x48
	v_lshl_add_u32 v101, v64, 7, s89
	v_lshl_add_u64 v[64:65], s[16:17], 0, v[56:57]
	v_lshlrev_b32_e32 v84, 4, v58
	v_lshl_or_b32 v152, s20, 5, v59
	v_lshl_add_u64 v[92:93], v[64:65], 0, s[72:73]
	s_lshl_b32 s72, s59, 6
	v_or_b32_e32 v60, s67, v60
	v_or_b32_e32 v177, s67, v63
	v_or_b32_e32 v179, s67, v66
	v_or_b32_e32 v181, s67, v68
	v_or_b32_e32 v182, s67, v70
	v_or_b32_e32 v184, s67, v73
	v_or_b32_e32 v188, s67, v75
	v_or_b32_e32 v190, s67, v77
	v_or_b32_e32 v192, s67, v79
	v_or_b32_e32 v194, s67, v82
	v_or_b32_e32 v196, s67, v154
	v_or_b32_e32 v198, s67, v156
	v_or_b32_e32 v200, s67, v158
	v_or_b32_e32 v202, s67, v161
	v_or_b32_e32 v204, s67, v163
	v_or_b32_e32 v206, s67, v165
	s_lshl_b32 s59, s59, 7
	v_lshlrev_b32_e32 v108, 1, v106
	v_lshlrev_b32_e32 v153, 1, v152
	v_or_b32_e32 v57, s72, v59
	v_or_b32_e32 v172, 32, v84
	v_or_b32_e32 v173, 64, v84
	v_or_b32_e32 v174, 0x60, v84
	v_cmp_gt_i32_e64 s[16:17], v152, v60
	v_cmp_gt_i32_e64 s[18:19], v152, v177
	v_cmp_gt_i32_e64 s[20:21], v152, v179
	v_cmp_gt_i32_e64 s[22:23], v152, v181
	v_cmp_gt_i32_e64 s[24:25], v152, v182
	v_cmp_gt_i32_e64 s[26:27], v152, v184
	v_cmp_gt_i32_e64 s[28:29], v152, v188
	v_cmp_gt_i32_e64 s[30:31], v152, v190
	v_cmp_gt_i32_e64 s[34:35], v152, v192
	v_cmp_gt_i32_e64 s[36:37], v152, v194
	v_cmp_gt_i32_e64 s[38:39], v152, v196
	v_cmp_gt_i32_e64 s[40:41], v152, v198
	v_cmp_gt_i32_e64 s[42:43], v152, v200
	v_cmp_gt_i32_e64 s[44:45], v152, v202
	v_cmp_gt_i32_e64 s[46:47], v152, v204
	v_cmp_gt_i32_e64 s[48:49], v152, v206
	v_xor_b32_e32 v152, s67, v166
	v_or_b32_e32 v220, s59, v56
	v_and_b32_e32 v107, 0xffffff0, v106
	v_or_b32_e32 v65, 15, v106
	v_lshlrev_b32_e32 v123, 7, v151
	v_bitop3_b32 v127, v167, v108, s83 bitop3:0x6c
	v_or_b32_e32 v112, 2, v151
	v_or_b32_e32 v117, 4, v151
	v_or_b32_e32 v122, 6, v151
	v_or_b32_e32 v129, 8, v151
	v_or_b32_e32 v134, 10, v151
	v_or_b32_e32 v139, 12, v151
	v_or_b32_e32 v144, 14, v151
	v_bitop3_b32 v175, s67, v153, v89 bitop3:0x6c
	v_xor_b32_e32 v183, s67, v71
	v_xor_b32_e32 v185, s67, v74
	v_xor_b32_e32 v189, s67, v76
	v_xor_b32_e32 v191, s67, v78
	v_bitop3_b32 v193, s67, v80, v79 bitop3:0x36
	v_xor_b32_e32 v195, s67, v83
	v_bitop3_b32 v197, s67, v155, v154 bitop3:0x36
	v_xor_b32_e32 v199, s67, v157
	v_bitop3_b32 v201, s67, v159, v158 bitop3:0x36
	v_xor_b32_e32 v203, s67, v162
	v_bitop3_b32 v205, s67, v164, v163 bitop3:0x36
	v_bitop3_b32 v207, v152, v153, s81 bitop3:0x6c
	v_bitop3_b32 v208, v171, v84, s83 bitop3:0x6c
	v_lshl_add_u32 v152, v57, 2, s90
; template <int MODE> __device__ __forceinline__ void chain(const bf16_t* __restrict__ U, bf16_t* __restrict__ OP, const float* __restrict__ hg_lb, int rowbase, int S, int h, int dir, int tau0, int nchunk, ...
;     ...
;         for (int e = 0; e < 2; ++e) { const int col = c0 + j + e; const float s0 = SEG[col], s1 = SEG[128 + col], s2 = SEG[256 + col];
;           const float off = (segt >= 1 ? s0 : 0.f) + (segt >= 2 ? s1 : 0.f) + (segt >= 3 ? s2 : 0.f);
;           g2[e] = GB[tau * GS + col] + off; gl2[e] = GB[63 * GS + col] + ((s0 + s1) + s2); }
;         if (MODE == 3) { const float ea = __builtin_amdgcn_exp2f(g2[0]), eb = __builtin_amdgcn_exp2f(g2[1]);
;           qh[j >> 1] = cvtpk(qq[j] * ea, qq[j + 1] * eb);
;           kh[j >> 1] = cvtpk(kk[j] * __builtin_amdgcn_exp2f(fminf(-g2[0], 115.f)), kk[j + 1] * __builtin_amdgcn_exp2f(fminf(-g2[1], 115.f))); }
;         const unsigned kt = cvtpk(kk[j] * __builtin_amdgcn_exp2f(gl2[0] - g2[0]), kk[j + 1] * __builtin_amdgcn_exp2f(gl2[1] - g2[1]));
;         *(bf16_t*)(KT + SWZ128(c0 + j, 2 * tau)) = (bf16_t)(kt & 0xffffu); *(bf16_t*)(KT + SWZ128(c0 + j + 1, 2 * tau)) = (bf16_t)(kt >> 16);
;         *(bf16_t*)(VT + SWZ128(c0 + j, 2 * tau)) = (bf16_t)vv[j >> 3][j & 7]; *(bf16_t*)(VT + SWZ128(c0 + j + 1, 2 * tau)) = (bf16_t)vv[(j + 1) >> 3][(j + 1) & 7];
;         if (tau == 63) { DD[c0 + j] = __builtin_amdgcn_exp2f(gl2[0]); DD[c0 + j + 1] = __builtin_amdgcn_exp2f(gl2[1]); }
;       }
;       if (MODE == 3) {
;       *(u32x4*)(QH + SWZ256(tau, 2 * c0)) = (u32x4){qh[0], qh[1], qh[2], qh[3]}; *(u32x4*)(QH + SWZ256(tau, 2 * c0 + 16)) = (u32x4){qh[4], qh[5], qh[6], qh[7]};
;       *(u32x4*)(KH + SWZ256(tau, 2 * c0)) = (u32x4){kh[0], kh[1], kh[2], kh[3]}; *(u32x4*)(KH + SWZ256(tau, 2 * c0 + 16)) = (u32x4){kh[4], kh[5], kh[6], kh[7]}; }
;     }
;     __syncthreads();
;     if (MODE == 3 && wid < 4 && wid != 1) { const int ti = wid >> 1, si = wid & 1; f32x16 a = f32x16{};
; #pragma unroll
;       for (int k8 = 0; k8 < 8; ++k8) { const int cb = (16 * k8 + 8 * hi) * 2;
;         const bf16x8 av = *(const bf16x8*)(QH + SWZ256(32 * ti + r32, cb)); const bf16x8 bv = *(const bf16x8*)(KH + SWZ256(32 * si + r32, cb));
;         a = __builtin_amdgcn_mfma_f32_32x32x16_bf16(av, bv, a, 0, 0, 0); }
; #pragma unroll
	v_bitop3_b32 v59, s72, v167, v59 bitop3:0x36
	v_lshl_add_u32 v209, v57, 7, s94
	v_bitop3_b32 v211, v171, v172, s83 bitop3:0x6c
	v_bitop3_b32 v213, v171, v173, s83 bitop3:0x6c
	v_bitop3_b32 v215, v171, v174, s83 bitop3:0x6c
	v_or_b32_e32 v171, 32, v57
	v_bitop3_b32 v57, v57, v167, 32 bitop3:0x36
	v_lshl_add_u32 v58, v58, 10, s58
	v_lshl_add_u32 v70, v70, 8, s58
	v_lshl_add_u32 v79, v79, 8, s58
	v_lshl_add_u32 v229, v154, 8, s58
	v_lshl_add_u32 v232, v158, 8, s58
	v_or_b32_e32 v154, 64, v220
	v_mul_lo_u32 v64, v107, s87
	v_mul_lo_u32 v65, v65, s87
	v_xad_u32 v128, v127, 16, v123
	v_lshlrev_b32_e32 v114, 2, v112
	v_xor_b32_e32 v132, 32, v127
	v_xad_u32 v133, v127, 48, v123
	v_lshlrev_b32_e32 v119, 2, v117
	v_xor_b32_e32 v137, 64, v127
	v_xad_u32 v138, v127, s82, v123
	v_lshlrev_b32_e32 v124, 2, v122
	v_xor_b32_e32 v142, 0x60, v127
	v_xad_u32 v143, v127, s83, v123
	v_lshlrev_b32_e32 v130, 2, v129
	v_lshlrev_b32_e32 v135, 2, v134
	v_lshlrev_b32_e32 v140, 2, v139
	v_lshlrev_b32_e32 v145, 2, v144
	v_xor_b32_e32 v176, v175, v61
	v_lshl_add_u32 v60, v60, 7, s86
	v_xor_b32_e32 v178, v175, v62
	v_lshl_add_u32 v177, v177, 7, s86
	v_xor_b32_e32 v180, v175, v67
	v_lshl_add_u32 v179, v179, 7, s86
	v_xor_b32_e32 v175, v175, v69
	v_lshl_add_u32 v181, v181, 7, s86
	v_bitop3_b32 v183, v183, v153, s81 bitop3:0x6c
	v_lshl_add_u32 v182, v182, 7, s86
	v_bitop3_b32 v185, v185, v153, s83 bitop3:0x6c
	v_lshl_add_u32 v184, v184, 7, s86
	v_bitop3_b32 v189, v189, v153, s81 bitop3:0x6c
	v_lshl_add_u32 v188, v188, 7, s86
	v_bitop3_b32 v191, v191, v153, s83 bitop3:0x6c
	v_lshl_add_u32 v190, v190, 7, s86
	v_bitop3_b32 v193, v193, v153, s83 bitop3:0x6c
	v_lshl_add_u32 v192, v192, 7, s86
	v_bitop3_b32 v195, v195, v153, s81 bitop3:0x6c
	v_lshl_add_u32 v194, v194, 7, s86
	v_bitop3_b32 v197, v197, v153, s83 bitop3:0x6c
	v_lshl_add_u32 v196, v196, 7, s86
	v_bitop3_b32 v199, v199, v153, s81 bitop3:0x6c
	v_lshl_add_u32 v198, v198, 7, s86
	v_bitop3_b32 v201, v201, v153, s83 bitop3:0x6c
	v_lshl_add_u32 v200, v200, 7, s86
	v_bitop3_b32 v203, v203, v153, s81 bitop3:0x6c
	v_lshl_add_u32 v202, v202, 7, s86
	v_bitop3_b32 v205, v205, v153, s83 bitop3:0x6c
	v_lshl_add_u32 v204, v204, 7, s86
	v_lshl_add_u32 v206, v206, 7, s86
	v_bitop3_b32 v210, v59, v84, s83 bitop3:0x6c
	v_bitop3_b32 v212, v59, v172, s83 bitop3:0x6c
	v_bitop3_b32 v214, v59, v173, s83 bitop3:0x6c
	v_bitop3_b32 v59, v59, v174, s83 bitop3:0x6c
	v_lshl_add_u32 v216, v171, 7, s94
	v_bitop3_b32 v217, v57, v84, s83 bitop3:0x6c
	v_bitop3_b32 v218, v57, v172, s83 bitop3:0x6c
	v_bitop3_b32 v219, v57, v173, s83 bitop3:0x6c
	v_bitop3_b32 v57, v57, v174, s83 bitop3:0x6c
	v_add_u32_e32 v221, v58, v61
	v_bitop3_b32 v222, v62, s59, v56 bitop3:0x1e
	v_lshl_add_u32 v63, v63, 8, s58
	v_bitop3_b32 v223, v67, s59, v56 bitop3:0x1e
	v_lshl_add_u32 v66, v66, 8, s58
	v_bitop3_b32 v56, v69, s59, v56 bitop3:0x1e
	v_lshl_add_u32 v68, v68, 8, s58
	v_add_u32_e32 v72, v70, v72
	v_bitop3_b32 v224, v74, v220, s82 bitop3:0x6c
	v_lshl_add_u32 v73, v73, 8, s58
	v_bitop3_b32 v225, v76, v220, s81 bitop3:0x6c
	v_lshl_add_u32 v75, v75, 8, s58
	v_bitop3_b32 v226, v78, v220, s83 bitop3:0x6c
	v_lshl_add_u32 v77, v77, 8, s58
	v_add_u32_e32 v81, v79, v81
	v_bitop3_b32 v227, v83, v220, s82 bitop3:0x6c
	v_lshl_add_u32 v82, v82, 8, s58
	v_bitop3_b32 v228, v155, v220, s81 bitop3:0x6c
	v_bitop3_b32 v230, v157, v220, s83 bitop3:0x6c
	v_lshl_add_u32 v231, v156, 8, s58
	v_add_u32_e32 v233, v232, v160
	v_bitop3_b32 v234, v162, v220, s82 bitop3:0x6c
	v_lshl_add_u32 v235, v161, 8, s58
	v_bitop3_b32 v236, v164, v220, s81 bitop3:0x6c
	v_lshl_add_u32 v237, v163, 8, s58
	v_bitop3_b32 v238, v166, v220, s83 bitop3:0x6c
	v_lshl_add_u32 v239, v165, 8, s58
	v_bitop3_b32 v61, v220, v61, 64 bitop3:0x36
	v_bitop3_b32 v62, v62, v220, 64 bitop3:0x1e
	v_bitop3_b32 v67, v67, v220, 64 bitop3:0x1e
	v_bitop3_b32 v69, v69, v220, 64 bitop3:0x1e
	v_bitop3_b32 v71, v71, v220, 64 bitop3:0x4e
	v_bitop3_b32 v74, v74, v154, s82 bitop3:0x6c
	v_bitop3_b32 v76, v76, v154, s81 bitop3:0x6c
	v_bitop3_b32 v78, v78, v154, s83 bitop3:0x6c
	v_bitop3_b32 v80, v80, v220, 64 bitop3:0x4e
	v_bitop3_b32 v83, v83, v154, s82 bitop3:0x6c
; __device__ __forceinline__ int crow(int r, int hi) { return (r & 3) + 8 * (r >> 2) + 4 * hi; }
; __device__ __forceinline__ int crow(int r, int hi) { return (r & 3) + 8 * (r >> 2) + 4 * hi; }
; __device__ __forceinline__ unsigned cvtpk_m(float lo, float hi) { f32x2_t v = {lo, hi}; bf16x2_t b = __builtin_convertvector(v, bf16x2_t); return __builtin_bit_cast(unsigned, b); }
; template <int MODE> __device__ __forceinline__ void chain(const bf16_t* __restrict__ U, bf16_t* __restrict__ OP, const float* __restrict__ hg_lb, int rowbase, int S, int h, int dir, int tau0, int nchunk, ...
;     ...
;   __syncthreads();
;     ...
;     { const int th = wid >> 2, vb = wid & 3;
;       if (MODE == 3) { f32x16 o = f32x16{};
;       const int nks = th ? 4 : 2;
;       for (int ks = 0; ks < nks; ++ks) { const int cb = (16 * ks + 8 * hi) * 2;
;         const bf16x8 av = *(const bf16x8*)(AL + SWZ128(32 * th + r32, cb)); const bf16x8 bv = *(const bf16x8*)(VT + SWZ128(32 * vb + r32, cb));
;         o = __builtin_amdgcn_mfma_f32_32x32x16_bf16(av, bv, o, 0, 0, 0); }
; #pragma unroll
;       for (int k8 = 0; k8 < 8; ++k8) { const int cb = (16 * k8 + 8 * hi) * 2;
;         const bf16x8 av = *(const bf16x8*)(QH + SWZ256(32 * th + r32, cb)); const bf16x8 bv = *(const bf16x8*)(ST + SWZ256(32 * vb + r32, cb));
;         o = __builtin_amdgcn_mfma_f32_32x32x16_bf16(av, bv, o, 0, 0, 0); }
; #pragma unroll
;       for (int r = 0; r < 16; ++r) { const int t2 = tau0 + ci * 64 + 32 * th + crow(r, hi); const int tok = dir ? (S - 1 - t2) : t2;
;         OPd[(size_t)(rowbase + tok) * 512 + h * 128 + 32 * vb + r32] = (bf16_t)(cvtpk_m(o[r], 0.f) & 0xffffu); }
;       } else { if (tid < 128) dseg *= DD[tid]; }
; #pragma unroll
;       for (int i = 0; i < 2; ++i) { const int kb = 2 * th + i; const float dk = DD[32 * kb + r32];
; #pragma unroll
;         for (int r = 0; r < 16; ++r) sacc[i][r] *= dk;
; #pragma unroll
;         for (int ks = 0; ks < 4; ++ks) { const int cb = (16 * ks + 8 * hi) * 2;
;           const bf16x8 av = *(const bf16x8*)(VT + SWZ128(32 * vb + r32, cb)); const bf16x8 bv = *(const bf16x8*)(KT + SWZ128(32 * kb + r32, cb));
;           sacc[i] = __builtin_amdgcn_mfma_f32_32x32x16_bf16(av, bv, sacc[i], 0, 0, 0); } }
	v_bitop3_b32 v240, v155, v154, s81 bitop3:0x6c
	v_bitop3_b32 v241, v157, v154, s83 bitop3:0x6c
	v_bitop3_b32 v242, v159, v220, 64 bitop3:0x4e
	v_bitop3_b32 v243, v162, v154, s82 bitop3:0x6c
	v_bitop3_b32 v244, v164, v154, s81 bitop3:0x6c
	v_bitop3_b32 v245, v166, v154, s83 bitop3:0x6c
	s_mov_b32 s66, 0
	v_add_u32_e32 v95, s85, v109
	v_cmp_eq_u32_e64 s[14:15], 63, v106
	v_bitop3_b32 v105, v84, v167, s83 bitop3:0x78
	v_add_u32_e32 v106, s88, v109
	v_add_u32_e32 v107, v127, v123
	v_add_u32_e32 v108, 0x80, v128
	v_add_u32_e32 v109, s90, v109
	v_add_u32_e32 v110, s88, v114
	v_add_u32_e32 v111, s86, v114
	v_lshl_add_u32 v112, v112, 7, v132
	v_add_u32_e32 v113, 0x180, v133
	v_add_u32_e32 v114, s90, v114
	v_add_u32_e32 v115, s88, v119
	v_add_u32_e32 v116, s86, v119
	v_lshl_add_u32 v117, v117, 7, v137
	v_add_u32_e32 v118, 0x280, v138
	v_add_u32_e32 v119, s90, v119
	v_add_u32_e32 v120, s88, v124
	v_add_u32_e32 v121, s86, v124
	v_lshl_add_u32 v122, v122, 7, v142
	v_add_u32_e32 v123, 0x380, v143
	v_add_u32_e32 v124, s90, v124
	v_add_u32_e32 v125, s88, v130
	v_add_u32_e32 v126, s86, v130
	v_lshl_add_u32 v127, v129, 7, v127
	v_add_u32_e32 v128, 0x480, v128
	v_add_u32_e32 v129, s90, v130
	v_add_u32_e32 v130, s88, v135
	v_add_u32_e32 v131, s86, v135
	v_lshl_add_u32 v132, v134, 7, v132
	v_add_u32_e32 v133, 0x580, v133
	v_add_u32_e32 v134, s90, v135
	v_add_u32_e32 v135, s88, v140
	v_add_u32_e32 v136, s86, v140
	v_lshl_add_u32 v137, v139, 7, v137
	v_add_u32_e32 v138, 0x680, v138
	v_add_u32_e32 v139, s90, v140
	v_add_u32_e32 v140, s88, v145
	v_add_u32_e32 v141, s86, v145
	v_lshl_add_u32 v142, v144, 7, v142
	v_add_u32_e32 v143, 0x780, v143
	v_add_u32_e32 v144, s90, v145
	v_bitop3_b32 v145, v84, v151, 32 bitop3:0x36
	v_bitop3_b32 v146, v84, v151, 64 bitop3:0x36
	v_bitop3_b32 v147, v84, v151, s81 bitop3:0x36
	v_bitop3_b32 v148, v84, v151, s3 bitop3:0x36
	v_bitop3_b32 v149, v84, v151, s91 bitop3:0x36
	v_bitop3_b32 v150, v84, v151, s92 bitop3:0x36
	v_bitop3_b32 v151, v84, v151, s93 bitop3:0x36
	v_lshl_add_u32 v153, v171, 2, s90
	s_lshl_b32 s72, s78, 1
	v_add_u32_e32 v154, v168, v64
	v_add_u32_e32 v155, v168, v65
	v_add_u32_e32 v156, 0, v169
	v_add_u32_e32 v157, 0, v170
	v_add_u32_e32 v158, v60, v176
	v_add_u32_e32 v159, v177, v178
	v_add_u32_e32 v160, v179, v180
	v_add_u32_e32 v161, v181, v175
	v_add_u32_e32 v162, v182, v183
	v_add_u32_e32 v163, v184, v185
	v_add_u32_e32 v164, v188, v189
	v_add_u32_e32 v165, v190, v191
	v_add_u32_e32 v166, v192, v193
	v_add_u32_e32 v167, v194, v195
	v_add_u32_e32 v168, v196, v197
	v_add_u32_e32 v169, v198, v199
	v_add_u32_e32 v170, v200, v201
	v_add_u32_e32 v171, v202, v203
	v_add_u32_e32 v172, v204, v205
	v_add_u32_e32 v173, v206, v207
	v_add_u32_e32 v174, v101, v208
	v_add_u32_e32 v175, v209, v210
	v_add_u32_e32 v176, v101, v211
	v_add_u32_e32 v177, v209, v212
	v_add_u32_e32 v178, v101, v213
	v_add_u32_e32 v179, v209, v214
	v_add_u32_e32 v180, v101, v215
	v_add_u32_e32 v181, v209, v59
	v_add_u32_e32 v182, v216, v217
	v_add_u32_e32 v183, v216, v218
	v_add_u32_e32 v184, v216, v219
	v_add_u32_e32 v185, v216, v57
	v_add_u32_e32 v188, v221, v220
	v_add_u32_e32 v189, v63, v222
	v_add_u32_e32 v190, v66, v223
	v_add_u32_e32 v191, v68, v56
	v_add_u32_e32 v192, v72, v220
	v_add_u32_e32 v193, v73, v224
	v_add_u32_e32 v194, v75, v225
	v_add_u32_e32 v195, v77, v226
	v_add_u32_e32 v196, v81, v220
	v_add_u32_e32 v197, v82, v227
	v_add_u32_e32 v198, v229, v228
	v_add_u32_e32 v199, v231, v230
	v_add_u32_e32 v200, v233, v220
	v_add_u32_e32 v201, v235, v234
	v_add_u32_e32 v202, v237, v236
	v_add_u32_e32 v203, v239, v238
	v_add_u32_e32 v204, v58, v61
	v_add_u32_e32 v205, v63, v62
	v_add_u32_e32 v206, v66, v67
	v_add_u32_e32 v207, v68, v69
	v_add_u32_e32 v208, v70, v71
	v_add_u32_e32 v209, v73, v74
	v_add_u32_e32 v210, v75, v76
	v_add_u32_e32 v211, v77, v78
	v_add_u32_e32 v212, v79, v80
	v_add_u32_e32 v213, v82, v83
	v_add_u32_e32 v214, v229, v240
	v_add_u32_e32 v215, v231, v241
	v_add_u32_e32 v216, v232, v242
	v_add_u32_e32 v217, v235, v243
	v_add_u32_e32 v218, v237, v244
	v_add_u32_e32 v219, v239, v245
	s_waitcnt lgkmcnt(0)
	s_barrier

; __device__ __forceinline__ int crow(int r, int hi) { return (r & 3) + 8 * (r >> 2) + 4 * hi; }
; __device__ __forceinline__ int crow(int r, int hi) { return (r & 3) + 8 * (r >> 2) + 4 * hi; }
; __device__ __forceinline__ unsigned cvtpk_m(float lo, float hi) { f32x2_t v = {lo, hi}; bf16x2_t b = __builtin_convertvector(v, bf16x2_t); return __builtin_bit_cast(unsigned, b); }
; template <int MODE> __device__ __forceinline__ void chain(const bf16_t* __restrict__ U, bf16_t* __restrict__ OP, const float* __restrict__ hg_lb, int rowbase, int S, int h, int dir, int tau0, int nchunk, ...
;     ...
;       for (int ks = 0; ks < nks; ++ks) { const int cb = (16 * ks + 8 * hi) * 2;
;         const bf16x8 av = *(const bf16x8*)(AL + SWZ128(32 * th + r32, cb)); const bf16x8 bv = *(const bf16x8*)(VT + SWZ128(32 * vb + r32, cb));
;         o = __builtin_amdgcn_mfma_f32_32x32x16_bf16(av, bv, o, 0, 0, 0); }
; #pragma unroll
;       for (int k8 = 0; k8 < 8; ++k8) { const int cb = (16 * k8 + 8 * hi) * 2;
;         const bf16x8 av = *(const bf16x8*)(QH + SWZ256(32 * th + r32, cb)); const bf16x8 bv = *(const bf16x8*)(ST + SWZ256(32 * vb + r32, cb));
;         o = __builtin_amdgcn_mfma_f32_32x32x16_bf16(av, bv, o, 0, 0, 0); }
; #pragma unroll
;       for (int r = 0; r < 16; ++r) { const int t2 = tau0 + ci * 64 + 32 * th + crow(r, hi); const int tok = dir ? (S - 1 - t2) : t2;
;         OPd[(size_t)(rowbase + tok) * 512 + h * 128 + 32 * vb + r32] = (bf16_t)(cvtpk_m(o[r], 0.f) & 0xffffu); }
;       } else { if (tid < 128) dseg *= DD[tid]; }
; #pragma unroll
;       for (int i = 0; i < 2; ++i) { const int kb = 2 * th + i; const float dk = DD[32 * kb + r32];
; #pragma unroll
;         for (int r = 0; r < 16; ++r) sacc[i][r] *= dk;
; #pragma unroll
;         for (int ks = 0; ks < 4; ++ks) { const int cb = (16 * ks + 8 * hi) * 2;
;           const bf16x8 av = *(const bf16x8*)(VT + SWZ128(32 * vb + r32, cb)); const bf16x8 bv = *(const bf16x8*)(KT + SWZ128(32 * kb + r32, cb));
;           sacc[i] = __builtin_amdgcn_mfma_f32_32x32x16_bf16(av, bv, sacc[i], 0, 0, 0); } }
.LBB0_843:
	v_xad_u32 v73, v72, v98, v99
	ds_read_b128 v[74:77], v73
	v_xad_u32 v73, v72, v100, v101
	ds_read_b128 v[78:81], v73
	s_add_i32 s58, s58, -1
	s_cmp_lg_u32 s58, 0
	v_add_u32_e32 v72, 32, v72
	s_waitcnt lgkmcnt(0)
	v_mfma_f32_32x32x16_bf16 v[32:47], v[74:77], v[78:81], v[32:47]
	s_cbranch_scc1 .LBB0_843
	v_add_u32_e32 v72, v102, v105
	ds_read_b128 v[72:75], v72 offset:32768
	v_add_u32_e32 v76, v103, v105
	ds_read_b128 v[80:83], v76
	v_add_u32_e32 v77, v102, v145
	v_add_u32_e32 v220, v103, v145
	ds_read_b128 v[76:79], v77 offset:32768
	ds_read_b32 v240, v152
	ds_read_b32 v242, v153
	v_add_u32_e32 v221, v103, v146
	v_add_u32_e32 v222, v103, v147
	v_add_u32_e32 v223, v102, v148
	s_waitcnt lgkmcnt(3)
	v_mfma_f32_32x32x16_bf16 v[32:47], v[72:75], v[80:83], v[32:47]
	ds_read_b128 v[72:75], v220
	v_add_u32_e32 v80, v102, v146
	ds_read_b128 v[80:83], v80 offset:32768
	v_add_u32_e32 v220, v102, v147
	v_add_u32_e32 v224, v103, v148
	v_add_u32_e32 v225, v102, v149
	v_add_u32_e32 v228, v103, v149
	s_waitcnt lgkmcnt(1)
	v_mfma_f32_32x32x16_bf16 v[32:47], v[76:79], v[72:75], v[32:47]
	ds_read_b128 v[72:75], v221
	ds_read_b128 v[76:79], v220 offset:32768
	v_add_u32_e32 v229, v102, v150
	v_add_u32_e32 v230, v103, v150
	v_add_u32_e32 v232, v102, v151
	v_add_u32_e32 v236, v103, v151
	v_lshl_add_u32 v241, s66, 6, v104
	s_waitcnt lgkmcnt(1)
	v_mfma_f32_32x32x16_bf16 v[32:47], v[80:83], v[72:75], v[32:47]
	ds_read_b128 v[72:75], v222
	ds_read_b128 v[80:83], v223 offset:32768
	ds_read_b128 v[220:223], v224
	ds_read_b128 v[224:227], v225 offset:32768
	v_sub_u32_e32 v245, s97, v241
	v_or_b32_e32 v244, 1, v241
	v_xad_u32 v243, v241, -1, s97
	v_cndmask_b32_e64 v246, v243, v241, s[6:7]
	v_add_u32_e32 v246, s96, v246
	v_ashrrev_i32_e32 v247, 31, v246
	v_lshlrev_b64 v[246:247], 10, v[246:247]
	v_lshl_add_u64 v[246:247], v[92:93], 0, v[246:247]
	v_pk_mul_f32 v[0:1], v[0:1], v[240:241] op_sel_hi:[1,0]
	v_pk_mul_f32 v[2:3], v[2:3], v[240:241] op_sel_hi:[1,0]
	s_waitcnt lgkmcnt(3)
	v_mfma_f32_32x32x16_bf16 v[32:47], v[76:79], v[72:75], v[32:47]
	ds_read_b128 v[72:75], v228
	ds_read_b128 v[76:79], v229 offset:32768
	ds_read_b128 v[228:231], v230
	ds_read_b128 v[232:235], v232 offset:32768
	ds_read_b128 v[236:239], v236
	v_pk_mul_f32 v[4:5], v[4:5], v[240:241] op_sel_hi:[1,0]
	v_pk_mul_f32 v[6:7], v[6:7], v[240:241] op_sel_hi:[1,0]
	v_pk_mul_f32 v[8:9], v[8:9], v[240:241] op_sel_hi:[1,0]
	v_pk_mul_f32 v[10:11], v[10:11], v[240:241] op_sel_hi:[1,0]
	v_pk_mul_f32 v[12:13], v[12:13], v[240:241] op_sel_hi:[1,0]
	v_pk_mul_f32 v[14:15], v[14:15], v[240:241] op_sel_hi:[1,0]
	s_waitcnt lgkmcnt(6)
	v_mfma_f32_32x32x16_bf16 v[32:47], v[80:83], v[220:223], v[32:47]
	s_waitcnt lgkmcnt(4)
	v_mfma_f32_32x32x16_bf16 v[32:47], v[224:227], v[72:75], v[32:47]
	s_waitcnt lgkmcnt(2)
	v_mfma_f32_32x32x16_bf16 v[32:47], v[76:79], v[228:231], v[32:47]
	s_waitcnt lgkmcnt(0)
	v_mfma_f32_32x32x16_bf16 v[32:47], v[232:235], v[236:239], v[32:47]
	ds_read_b128 v[72:75], v174
	v_mul_f32_e64 v16, v16, v242
	v_mul_f32_e64 v17, v17, v242
	v_pk_mul_f32 v[18:19], v[18:19], v[242:243] op_sel_hi:[1,0]
	v_pk_mul_f32 v[20:21], v[20:21], v[242:243] op_sel_hi:[1,0]
	v_pk_mul_f32 v[22:23], v[22:23], v[242:243] op_sel_hi:[1,0]
	s_nop 5
	v_cvt_pk_bf16_f32 v32, v32, s0
	v_cvt_pk_bf16_f32 v33, v33, s0
	v_cvt_pk_bf16_f32 v34, v34, s0
	global_store_short v[246:247], v32, off
	v_lshl_add_u64 v[246:247], v[246:247], 0, v[248:249]
	global_store_short v[246:247], v33, off
	v_lshl_add_u64 v[246:247], v[246:247], 0, v[248:249]
	global_store_short v[246:247], v34, off
	v_cvt_pk_bf16_f32 v35, v35, s0
	v_lshl_add_u64 v[246:247], v[246:247], 0, v[248:249]
	global_store_short v[246:247], v35, off
	v_cvt_pk_bf16_f32 v34, v36, s0
	v_lshl_add_u64 v[246:247], v[246:247], 0, v[250:251]
	global_store_short v[246:247], v34, off
	v_cvt_pk_bf16_f32 v34, v37, s0
	v_lshl_add_u64 v[246:247], v[246:247], 0, v[248:249]
	global_store_short v[246:247], v34, off
	v_cvt_pk_bf16_f32 v34, v38, s0
	v_lshl_add_u64 v[246:247], v[246:247], 0, v[248:249]
	global_store_short v[246:247], v34, off
	v_cvt_pk_bf16_f32 v34, v39, s0
	v_lshl_add_u64 v[246:247], v[246:247], 0, v[248:249]
	global_store_short v[246:247], v34, off
	v_cvt_pk_bf16_f32 v34, v40, s0
	v_lshl_add_u64 v[246:247], v[246:247], 0, v[250:251]
	global_store_short v[246:247], v34, off
	v_cvt_pk_bf16_f32 v34, v41, s0
	v_lshl_add_u64 v[246:247], v[246:247], 0, v[248:249]
	global_store_short v[246:247], v34, off
	v_cvt_pk_bf16_f32 v34, v42, s0
	v_lshl_add_u64 v[246:247], v[246:247], 0, v[248:249]
	global_store_short v[246:247], v34, off
	v_cvt_pk_bf16_f32 v34, v43, s0
	v_lshl_add_u64 v[246:247], v[246:247], 0, v[248:249]
	global_store_short v[246:247], v34, off
	ds_read_b128 v[32:35], v175
	ds_read_b128 v[36:39], v176
	s_waitcnt lgkmcnt(1)
	v_mfma_f32_32x32x16_bf16 v[0:15], v[72:75], v[32:35], v[0:15]
	ds_read_b128 v[32:35], v177
	ds_read_b128 v[40:43], v178
	v_cvt_pk_bf16_f32 v44, v44, s0
	s_waitcnt lgkmcnt(1)
	v_mfma_f32_32x32x16_bf16 v[0:15], v[36:39], v[32:35], v[0:15]
	v_lshl_add_u64 v[246:247], v[246:247], 0, v[250:251]
	global_store_short v[246:247], v44, off
	ds_read_b128 v[32:35], v179
	v_cvt_pk_bf16_f32 v80, v45, s0
	ds_read_b128 v[76:79], v180
	s_waitcnt lgkmcnt(1)
	v_mfma_f32_32x32x16_bf16 v[0:15], v[40:43], v[32:35], v[0:15]
	ds_read_b128 v[32:35], v181
	v_lshl_add_u64 v[246:247], v[246:247], 0, v[248:249]
	global_store_short v[246:247], v80, off
	ds_read_b128 v[80:83], v182
	v_mul_f32_e64 v24, v24, v242
	v_mul_f32_e64 v25, v25, v242
	v_pk_mul_f32 v[26:27], v[26:27], v[242:243] op_sel_hi:[1,0]
	v_pk_mul_f32 v[28:29], v[28:29], v[242:243] op_sel_hi:[1,0]
	v_pk_mul_f32 v[30:31], v[30:31], v[242:243] op_sel_hi:[1,0]
	s_waitcnt lgkmcnt(1)
	v_mfma_f32_32x32x16_bf16 v[0:15], v[76:79], v[32:35], v[0:15]
	ds_read_b128 v[32:35], v183
	v_cvt_pk_bf16_f32 v46, v46, s0
	s_waitcnt lgkmcnt(1)
	v_mfma_f32_32x32x16_bf16 v[16:31], v[72:75], v[80:83], v[16:31]
	ds_read_b128 v[72:75], v184
	s_cmp_lg_u32 s67, 16
	s_mov_b32 s66, s67
	s_waitcnt lgkmcnt(1)
	v_mfma_f32_32x32x16_bf16 v[16:31], v[36:39], v[32:35], v[16:31]
	v_lshl_add_u64 v[246:247], v[246:247], 0, v[248:249]
	global_store_short v[246:247], v46, off
	s_waitcnt lgkmcnt(0)
	v_mfma_f32_32x32x16_bf16 v[16:31], v[40:43], v[72:75], v[16:31]
	ds_read_b128 v[32:35], v185
	v_cvt_pk_bf16_f32 v38, v47, s0
	v_lshl_add_u64 v[246:247], v[246:247], 0, v[248:249]
	global_store_short v[246:247], v38, off
	s_waitcnt lgkmcnt(0)
	v_mfma_f32_32x32x16_bf16 v[16:31], v[76:79], v[32:35], v[16:31]
	s_barrier
; __device__ __forceinline__ int crow(int r, int hi) { return (r & 3) + 8 * (r >> 2) + 4 * hi; }
; __device__ __forceinline__ unsigned cvtpk(float lo, float hi) { unsigned r; asm volatile("v_cvt_pk_bf16_f32 %0, %1, %2" : "=v"(r) : "v"(lo), "v"(hi)); return r; }
; __device__ __forceinline__ int crow(int r, int hi) { return (r & 3) + 8 * (r >> 2) + 4 * hi; }
; __device__ __forceinline__ unsigned cvtpk(float lo, float hi) { unsigned r; asm volatile("v_cvt_pk_bf16_f32 %0, %1, %2" : "=v"(r) : "v"(lo), "v"(hi)); return r; }
; template <int MODE> __device__ __forceinline__ void chain(const bf16_t* __restrict__ U, bf16_t* __restrict__ OP, const float* __restrict__ hg_lb, int rowbase, int S, int h, int dir, int tau0, int nchunk, ...
;     ...
;   for (int ci = 0; ci < nchunk; ++ci) {
;     const bf16x8 qv[2] = {nq0, nq1}, vv[2] = {nv0, nv1}, fv[2] = {nf0, nf1};
;     { const int cn = (ci + 1 < nchunk) ? ci + 1 : ci; const int t2 = tau0 + cn * 64 + tau; const int tok = dir ? (S - 1 - t2) : t2; const bf16_t* p = Ub + (size_t)tok * 2560;
;       if (MODE == 3) { nq0 = *(const bf16x8*)(p + offq); nq1 = *(const bf16x8*)(p + offq + 8); } nv0 = *(const bf16x8*)(p + offv); nv1 = *(const bf16x8*)(p + offv + 8); nf0 = *(const bf16x8*)(p + offf); nf1 = *(const bf16x8*)(p + offf + 8); }
;     ...
;     if (MODE == 3) { const int th = wid >> 2, vb = wid & 3;
; #pragma unroll
;       for (int i = 0; i < 2; ++i) { const int kb = 2 * th + i;
; #pragma unroll
;         for (int r = 0; r < 16; ++r) *(bf16_t*)(ST + SWZ256(32 * vb + crow(r, hi), 2 * (32 * kb + r32))) = (bf16_t)(cvtpk(sacc[i][r], 0.f) & 0xffffu); } }
	v_cvt_pk_bf16_f32 v32, v0, v85
	ds_write_b16 v188, v32
	v_cvt_pk_bf16_f32 v32, v1, v85
	ds_write_b16 v189, v32
	v_cvt_pk_bf16_f32 v32, v2, v85
	ds_write_b16 v190, v32
	v_cvt_pk_bf16_f32 v32, v3, v85
	ds_write_b16 v191, v32
	v_cvt_pk_bf16_f32 v32, v4, v85
	ds_write_b16 v192, v32
	v_cvt_pk_bf16_f32 v32, v5, v85
	ds_write_b16 v193, v32
	v_cvt_pk_bf16_f32 v32, v6, v85
	ds_write_b16 v194, v32
	v_cvt_pk_bf16_f32 v32, v7, v85
	ds_write_b16 v195, v32
	v_cvt_pk_bf16_f32 v32, v8, v85
	ds_write_b16 v196, v32
	v_cvt_pk_bf16_f32 v32, v9, v85
	ds_write_b16 v197, v32
	v_cvt_pk_bf16_f32 v32, v10, v85
	ds_write_b16 v198, v32
	v_cvt_pk_bf16_f32 v32, v11, v85
	ds_write_b16 v199, v32
	v_cvt_pk_bf16_f32 v32, v12, v85
	ds_write_b16 v200, v32
	v_cvt_pk_bf16_f32 v32, v13, v85
	ds_write_b16 v201, v32
	v_cvt_pk_bf16_f32 v32, v14, v85
	ds_write_b16 v202, v32
	v_cvt_pk_bf16_f32 v32, v15, v85
	ds_write_b16 v203, v32
	v_cvt_pk_bf16_f32 v32, v16, v85
	ds_write_b16 v204, v32
	v_cvt_pk_bf16_f32 v32, v17, v85
	ds_write_b16 v205, v32
	v_cvt_pk_bf16_f32 v32, v18, v85
	ds_write_b16 v206, v32
	v_cvt_pk_bf16_f32 v32, v19, v85
	ds_write_b16 v207, v32
	v_cvt_pk_bf16_f32 v32, v20, v85
	ds_write_b16 v208, v32
	v_cvt_pk_bf16_f32 v32, v21, v85
	ds_write_b16 v209, v32
	v_cvt_pk_bf16_f32 v32, v22, v85
	ds_write_b16 v210, v32
	v_cvt_pk_bf16_f32 v32, v23, v85
	ds_write_b16 v211, v32
	v_cvt_pk_bf16_f32 v32, v24, v85
	ds_write_b16 v212, v32
	v_cvt_pk_bf16_f32 v32, v25, v85
	ds_write_b16 v213, v32
	v_cvt_pk_bf16_f32 v32, v26, v85
	ds_write_b16 v214, v32
	v_cvt_pk_bf16_f32 v32, v27, v85
	ds_write_b16 v215, v32
	v_cvt_pk_bf16_f32 v32, v28, v85
	ds_write_b16 v216, v32
	v_cvt_pk_bf16_f32 v32, v29, v85
	ds_write_b16 v217, v32
	v_cvt_pk_bf16_f32 v32, v30, v85
	ds_write_b16 v218, v32
	v_cvt_pk_bf16_f32 v32, v31, v85
	ds_write_b16 v219, v32
	s_waitcnt vmcnt(21)
	v_mov_b64_e32 v[44:45], v[56:57]
	s_waitcnt vmcnt(20)
	v_mov_b64_e32 v[36:37], v[60:61]
	s_waitcnt vmcnt(19)
	v_mov_b64_e32 v[40:41], v[64:65]
	s_waitcnt vmcnt(18)
	v_mov_b64_e32 v[32:33], v[68:69]
	v_mov_b64_e32 v[46:47], v[58:59]
	v_mov_b64_e32 v[38:39], v[62:63]
	v_mov_b64_e32 v[42:43], v[66:67]
	v_mov_b64_e32 v[34:35], v[70:71]
	s_cbranch_scc1 .LBB0_824
	s_add_i32 s74, s74, s33
	s_cmpk_gt_i32 s74, 0x2ff
	s_waitcnt lgkmcnt(0)
	s_barrier
	s_cbranch_scc0 .LBB0_814
	s_branch .LBB0_847
